# norm1/norm2 phases hand-written: one wave normalises 4 consecutive rows per step (16 row loads + 12 parameter loads in flight together, DPP row reductions, g*(1+scale) formed once per quad), replacing
# speedup vs baseline: 1.0124x; 1.0124x over previous
; DI unsigned xb_add(unsigned* p, unsigned v) { return __hip_atomic_fetch_add(p, v, __ATOMIC_RELAXED, __HIP_MEMORY_SCOPE_AGENT); }
; DI void xcd_barrier(const XcdBarrier& b) {
;   asm volatile("s_waitcnt vmcnt(0)" ::: "memory");
;   __syncthreads();
;   if (threadIdx.x == 0) {
;     unsigned* bar = b.bar;
;     __builtin_amdgcn_s_waitcnt(0);
;     unsigned nloc = b.st[0], nx = b.st[1];
;     if (nloc == 0u) { xcd_barrier_complete(bar, b.x, nloc, nx); b.st[0] = nloc; b.st[1] = nx; }
;     const unsigned old = xb_add(&bar[XB_XSUB(b.x)], 1u);
; __global__ void __launch_bounds__(THREADS, 2) fwd_megakernel(Params p) {
;     ...
;     phase_norm(p, layer, 0, NTOK);
;     xcd_barrier(xb);
.LBB0_333:
	s_mov_b32 s100, 0
	s_mov_b32 s101, s34
	s_branch .Lnm_entry
.Lnm_ret0:
.LBB0_334:
	s_movk_i32 s94, 0x43ff
	s_or_b64 exec, exec, s[10:11]
	s_xor_b64 s[0:1], s[6:7], -1
	v_writelane_b32 v234, s0, 48
	s_waitcnt vmcnt(0)
	s_barrier
	s_nop 0
	v_writelane_b32 v234, s1, 49
	s_nop 0
	v_readlane_b32 s0, v234, 23
	v_readlane_b32 s1, v234, 24
	s_xor_b64 s[0:1], s[0:1], -1
	v_writelane_b32 v234, s0, 50
	s_nop 1
	v_writelane_b32 v234, s1, 51
	s_mov_b64 s[0:1], exec
	v_readlane_b32 s6, v236, 2
	v_readlane_b32 s7, v236, 3
	v_readlane_b32 s80, v234, 34
	s_and_b64 s[6:7], s[0:1], s[6:7]
	s_mov_b32 s52, s34
	v_readlane_b32 s81, v234, 35
	s_mov_b64 exec, s[6:7]
	s_cbranch_execz .LBB0_382
	s_waitcnt vmcnt(0) expcnt(0) lgkmcnt(0)
	ds_read_b32 v2, v188
	ds_read_b32 v0, v189
	s_waitcnt lgkmcnt(1)
	v_cmp_ne_u32_e32 vcc, 0, v2
	s_cbranch_vccnz .LBB0_350
	s_mov_b32 s28, 1
	s_branch .LBB0_338

; DI unsigned xb_add(unsigned* p, unsigned v) { return __hip_atomic_fetch_add(p, v, __ATOMIC_RELAXED, __HIP_MEMORY_SCOPE_AGENT); }
; DI void xcd_barrier(const XcdBarrier& b) {
;   asm volatile("s_waitcnt vmcnt(0)" ::: "memory");
;   __syncthreads();
;   if (threadIdx.x == 0) {
;     unsigned* bar = b.bar;
;     __builtin_amdgcn_s_waitcnt(0);
;     unsigned nloc = b.st[0], nx = b.st[1];
;     if (nloc == 0u) { xcd_barrier_complete(bar, b.x, nloc, nx); b.st[0] = nloc; b.st[1] = nx; }
;     const unsigned old = xb_add(&bar[XB_XSUB(b.x)], 1u);
; __global__ void __launch_bounds__(THREADS, 2) fwd_megakernel(Params p) {
;     ...
;     phase_norm(p, layer, 1, MT_RES * 128);
;     xcd_barrier(xb);
.LBB0_1596:
	s_mov_b32 s100, 1
	s_mov_b32 s101, s52
	s_branch .Lnm_entry
.Lnm_ret1:
.LBB0_1597:
	s_or_b64 exec, exec, s[10:11]
	s_waitcnt vmcnt(0)
	s_barrier
	s_mov_b64 s[0:1], exec
	v_readlane_b32 s10, v236, 2
	v_readlane_b32 s11, v236, 3
	s_and_b64 s[10:11], s[0:1], s[10:11]
	s_mov_b64 exec, s[10:11]
	s_cbranch_execz .LBB0_1645
	s_waitcnt vmcnt(0) expcnt(0) lgkmcnt(0)
	ds_read_b32 v2, v188
	ds_read_b32 v0, v189
	s_waitcnt lgkmcnt(1)
	v_cmp_ne_u32_e32 vcc, 0, v2
	s_cbranch_vccnz .LBB0_1613
	s_mov_b32 s28, 1
	s_branch .LBB0_1601

; DI int get_tid() { int t = threadIdx.x; asm volatile("" : "+v"(t)); return t; }
; DI void phase_norm(const Params& p, int layer, int which  , int nrows) {
;   const int lane = get_tid() & 63, gw = blockIdx.x * 4 + (get_tid() >> 6), nw = gridDim.x * 4;
;   const float* g = (which == 0 ? p.norm1_g : p.norm2_g) + layer * D;
;   const float* mod = (const float*)(p.ws + OFF_MOD) + (size_t)layer * 9 * 6144;
;   bf16_t* H = (bf16_t*)(p.ws + OFF_H);
;   const bool first = (which == 0) && layer == 0;
;   for (int pr = gw; pr < (nrows >> 1); pr += nw) {
;     const int row = pr * 2;
;     const float* xr0 = xold_ptr(p, layer, first, row);
;     const float* xr1 = xold_ptr(p, layer, first, row + 1);
;     const int b9 = row < NLAT ? (row >> 12) : 8;
;     float4 v[2][4];
;     float ss0 = 0.f, ss1 = 0.f;
; #pragma unroll
;     for (int i = 0; i < 4; ++i) {
;       typedef float f4ld __attribute__((ext_vector_type(4)));
;       const f4ld a_ = __builtin_nontemporal_load((const f4ld*)xr0 + lane + 64 * i), b_ = __builtin_nontemporal_load((const f4ld*)xr1 + lane + 64 * i);
;       v[0][i] = make_float4(a_[0], a_[1], a_[2], a_[3]); v[1][i] = make_float4(b_[0], b_[1], b_[2], b_[3]);
;     }
;     const float* sh = mod + b9 * 6144 + (which == 0 ? 0 : 3) * 1024;
;     const float* sc = sh + 1024;
;     float4 gg[4], s4[4], h4[4];
; #pragma unroll
;     for (int i = 0; i < 4; ++i) {
;       const int col = 4 * (lane + 64 * i);
;       gg[i] = *(const float4*)(g + col); s4[i] = *(const float4*)(sc + col); h4[i] = *(const float4*)(sh + col);
;     }
.Lnm_entry:
	v_writelane_b32 v254, s52, 0
	v_writelane_b32 v254, s53, 1
	v_writelane_b32 v254, s54, 2
	v_writelane_b32 v254, s55, 3
	v_writelane_b32 v254, s56, 4
	v_writelane_b32 v254, s57, 5
	v_writelane_b32 v254, s58, 6
	v_writelane_b32 v254, s59, 7
	v_writelane_b32 v254, s60, 8
	v_writelane_b32 v254, s61, 9
	v_writelane_b32 v254, s62, 10
	v_writelane_b32 v254, s63, 11
	v_writelane_b32 v254, s64, 12
	v_writelane_b32 v254, s65, 13
	v_writelane_b32 v254, s66, 14
	v_writelane_b32 v254, s67, 15
	v_writelane_b32 v254, s68, 16
	v_writelane_b32 v254, s69, 17
	v_writelane_b32 v254, s70, 18
	v_writelane_b32 v254, s71, 19
	v_writelane_b32 v254, s72, 20
	v_writelane_b32 v254, s73, 21
	v_writelane_b32 v254, s74, 22
	v_writelane_b32 v254, s75, 23
	v_writelane_b32 v254, s76, 24
	v_writelane_b32 v254, s77, 25
	v_writelane_b32 v254, s78, 26
	v_writelane_b32 v254, s79, 27
	v_writelane_b32 v254, s80, 28
	v_writelane_b32 v254, s81, 29
	v_writelane_b32 v254, s82, 30
	v_writelane_b32 v254, s83, 31
	v_writelane_b32 v254, s84, 32
	v_writelane_b32 v254, s85, 33
	v_writelane_b32 v254, s86, 34
	v_writelane_b32 v254, s87, 35
	v_writelane_b32 v254, s88, 36
	v_writelane_b32 v254, s89, 37
	v_writelane_b32 v254, s90, 38
	v_writelane_b32 v254, s91, 39
	s_mov_b32 s52, s100
	s_mov_b32 s53, s101
	v_lshrrev_b32_e32 v116, 6, v143
	v_readlane_b32 s0, v255, 0
	s_nop 0
	v_readfirstlane_b32 s1, v116
	s_nop 3
	s_lshl_b32 s54, s0, 2
	s_add_u32 s54, s54, s1
	s_lshl_b32 s56, s26, 2
	s_movk_i32 s55, 8704
	s_cmp_eq_u32 s52, 1
	s_cbranch_scc0 .Lnm_nq_1
	s_cmp_eq_u32 s53, 0
	s_cbranch_scc1 .Lnm_nq_1
	s_movk_i32 s55, 8192
.Lnm_nq_1:
	s_mov_b32 s60, s22
	s_mov_b32 s61, s23
	s_add_u32 s62, s24, 0x19d80000
	s_addc_u32 s63, s25, 0
	v_readlane_b32 s76, v255, 1
	v_readlane_b32 s77, v255, 2
	s_nop 3
	s_or_b32 s0, s52, s53
	s_cmp_eq_u32 s0, 0
	s_cbranch_scc0 .Lnm_nf_2
	s_load_dwordx2 s[60:61], s[76:77], 0x0
	s_load_dwordx2 s[62:63], s[76:77], 0x10
.Lnm_nf_2:
	s_cmp_eq_u32 s52, 1
	s_cbranch_scc1 .Lnm_g1_3
	s_load_dwordx2 s[68:69], s[76:77], 0x30
	s_branch .Lnm_gj_4
.Lnm_g1_3:
	s_load_dwordx2 s[68:69], s[76:77], 0x38
.Lnm_gj_4:
	s_waitcnt lgkmcnt(0)
	s_lshl_b32 s0, s53, 12
	s_add_u32 s68, s68, s0
	s_addc_u32 s69, s69, 0
	s_mul_i32 s0, s53, 221184
	s_mul_i32 s1, s52, 12288
	s_add_u32 s0, s0, s1
	s_add_u32 s0, s0, 0x1d300000
	s_add_u32 s70, s24, s0
	s_addc_u32 s71, s25, 0
	v_and_b32_e32 v116, 63, v143
	v_lshlrev_b32_e32 v152, 4, v116
	v_mov_b32_e32 v144, v152
	v_add_u32_e32 v145, 0x1000, v152
	v_add_u32_e32 v146, 0x2000, v152
	v_add_u32_e32 v147, 0x3000, v152
	v_lshrrev_b32_e32 v117, 3, v116
	s_mov_b32 s0, 0x220000
	v_mul_lo_u32 v117, v117, s0
	v_and_b32_e32 v118, 7, v116
	v_lshl_add_u32 v148, v118, 3, v117
	v_add_u32_e32 v149, 0x1100000, v148
	v_add_u32_e32 v150, 0x1100000, v149
	v_add_u32_e32 v151, 0x1100000, v150
	v_mov_b32_e32 v153, 0x358637bd
.Lnm_loop_5:
	s_cmp_ge_u32 s54, s55
	s_cbranch_scc1 .Lnm_done_6
	s_lshl_b32 s57, s54, 2
	s_cmp_lt_u32 s57, 0x8000
	s_cbranch_scc0 .Lnm_ctx_7
	s_lshl_b32 s0, s57, 12
	s_add_u32 s64, s60, s0
	s_addc_u32 s65, s61, 0
	s_lshr_b32 s1, s57, 12
	s_branch .Lnm_j_8
.Lnm_ctx_7:
	s_sub_u32 s0, s57, 0x8000
	s_lshl_b32 s0, s0, 12
	s_add_u32 s64, s62, s0
	s_addc_u32 s65, s63, 0
	s_mov_b32 s1, 8
.Lnm_j_8:
	s_mul_i32 s1, s1, 24576
	s_add_u32 s72, s70, s1
	s_addc_u32 s73, s71, 0
	s_add_u32 s74, s72, 0x1000
	s_addc_u32 s75, s73, 0
	s_lshl_b32 s0, s57, 6
	s_add_u32 s0, s0, 0x15980000
	s_add_u32 s66, s24, s0
	s_addc_u32 s67, s25, 0
	global_load_dwordx4 v[0:3], v144, s[64:65] offset:0 nt
	global_load_dwordx4 v[4:7], v144, s[64:65] offset:1024 nt
	global_load_dwordx4 v[8:11], v144, s[64:65] offset:2048 nt
	global_load_dwordx4 v[12:15], v144, s[64:65] offset:3072 nt
	global_load_dwordx4 v[16:19], v145, s[64:65] offset:0 nt
	global_load_dwordx4 v[20:23], v145, s[64:65] offset:1024 nt
	global_load_dwordx4 v[24:27], v145, s[64:65] offset:2048 nt
	global_load_dwordx4 v[28:31], v145, s[64:65] offset:3072 nt
	global_load_dwordx4 v[32:35], v146, s[64:65] offset:0 nt
	global_load_dwordx4 v[36:39], v146, s[64:65] offset:1024 nt
	global_load_dwordx4 v[40:43], v146, s[64:65] offset:2048 nt
	global_load_dwordx4 v[44:47], v146, s[64:65] offset:3072 nt
	global_load_dwordx4 v[48:51], v147, s[64:65] offset:0 nt
	global_load_dwordx4 v[52:55], v147, s[64:65] offset:1024 nt
	global_load_dwordx4 v[56:59], v147, s[64:65] offset:2048 nt
	global_load_dwordx4 v[60:63], v147, s[64:65] offset:3072 nt
	global_load_dwordx4 v[64:67], v152, s[68:69] offset:0
	global_load_dwordx4 v[68:71], v152, s[68:69] offset:1024
	global_load_dwordx4 v[72:75], v152, s[68:69] offset:2048
	global_load_dwordx4 v[76:79], v152, s[68:69] offset:3072
	global_load_dwordx4 v[80:83], v152, s[74:75] offset:0
	global_load_dwordx4 v[84:87], v152, s[74:75] offset:1024
	global_load_dwordx4 v[88:91], v152, s[74:75] offset:2048
	global_load_dwordx4 v[92:95], v152, s[74:75] offset:3072
	global_load_dwordx4 v[96:99], v152, s[72:73] offset:0
	global_load_dwordx4 v[100:103], v152, s[72:73] offset:1024
	global_load_dwordx4 v[104:107], v152, s[72:73] offset:2048
	global_load_dwordx4 v[108:111], v152, s[72:73] offset:3072
	s_waitcnt vmcnt(24)
	v_mul_f32_e32 v112, v0, v0
	v_fmac_f32_e32 v112, v1, v1
	v_fmac_f32_e32 v112, v2, v2
	v_fmac_f32_e32 v112, v3, v3
	v_fmac_f32_e32 v112, v4, v4
	v_fmac_f32_e32 v112, v5, v5
	v_fmac_f32_e32 v112, v6, v6
	v_fmac_f32_e32 v112, v7, v7
	v_fmac_f32_e32 v112, v8, v8
	v_fmac_f32_e32 v112, v9, v9
	v_fmac_f32_e32 v112, v10, v10
	v_fmac_f32_e32 v112, v11, v11
	v_fmac_f32_e32 v112, v12, v12
	v_fmac_f32_e32 v112, v13, v13
	v_fmac_f32_e32 v112, v14, v14
	v_fmac_f32_e32 v112, v15, v15
	s_waitcnt vmcnt(20)
; DI void phase_norm(const Params& p, int layer, int which  , int nrows) {
;     ...
; #pragma unroll
;     for (int i = 0; i < 4; ++i) {
;       ss0 += v[0][i].x * v[0][i].x + v[0][i].y * v[0][i].y + v[0][i].z * v[0][i].z + v[0][i].w * v[0][i].w;
;       ss1 += v[1][i].x * v[1][i].x + v[1][i].y * v[1][i].y + v[1][i].z * v[1][i].z + v[1][i].w * v[1][i].w;
;     }
;     ss0 = wave_sum(ss0); ss1 = wave_sum(ss1);
;     const float rstd0 = rsqrtf(ss0 * (1.0f / D) + 1e-6f), rstd1 = rsqrtf(ss1 * (1.0f / D) + 1e-6f);
	v_mul_f32_e32 v113, v16, v16
	v_fmac_f32_e32 v113, v17, v17
	v_fmac_f32_e32 v113, v18, v18
	v_fmac_f32_e32 v113, v19, v19
	v_fmac_f32_e32 v113, v20, v20
	v_fmac_f32_e32 v113, v21, v21
	v_fmac_f32_e32 v113, v22, v22
	v_fmac_f32_e32 v113, v23, v23
	v_fmac_f32_e32 v113, v24, v24
	v_fmac_f32_e32 v113, v25, v25
	v_fmac_f32_e32 v113, v26, v26
	v_fmac_f32_e32 v113, v27, v27
	v_fmac_f32_e32 v113, v28, v28
	v_fmac_f32_e32 v113, v29, v29
	v_fmac_f32_e32 v113, v30, v30
	v_fmac_f32_e32 v113, v31, v31
	s_waitcnt vmcnt(16)
	v_mul_f32_e32 v114, v32, v32
	v_fmac_f32_e32 v114, v33, v33
	v_fmac_f32_e32 v114, v34, v34
	v_fmac_f32_e32 v114, v35, v35
	v_fmac_f32_e32 v114, v36, v36
	v_fmac_f32_e32 v114, v37, v37
	v_fmac_f32_e32 v114, v38, v38
	v_fmac_f32_e32 v114, v39, v39
	v_fmac_f32_e32 v114, v40, v40
	v_fmac_f32_e32 v114, v41, v41
	v_fmac_f32_e32 v114, v42, v42
	v_fmac_f32_e32 v114, v43, v43
	v_fmac_f32_e32 v114, v44, v44
	v_fmac_f32_e32 v114, v45, v45
	v_fmac_f32_e32 v114, v46, v46
	v_fmac_f32_e32 v114, v47, v47
	s_waitcnt vmcnt(12)
	v_mul_f32_e32 v115, v48, v48
	v_fmac_f32_e32 v115, v49, v49
	v_fmac_f32_e32 v115, v50, v50
	v_fmac_f32_e32 v115, v51, v51
	v_fmac_f32_e32 v115, v52, v52
	v_fmac_f32_e32 v115, v53, v53
	v_fmac_f32_e32 v115, v54, v54
	v_fmac_f32_e32 v115, v55, v55
	v_fmac_f32_e32 v115, v56, v56
	v_fmac_f32_e32 v115, v57, v57
	v_fmac_f32_e32 v115, v58, v58
	v_fmac_f32_e32 v115, v59, v59
	v_fmac_f32_e32 v115, v60, v60
	v_fmac_f32_e32 v115, v61, v61
	v_fmac_f32_e32 v115, v62, v62
	v_fmac_f32_e32 v115, v63, v63
	v_add_f32_dpp v112, v112, v112 quad_perm:[1,0,3,2] row_mask:0xf bank_mask:0xf
	v_add_f32_dpp v113, v113, v113 quad_perm:[1,0,3,2] row_mask:0xf bank_mask:0xf
	v_add_f32_dpp v114, v114, v114 quad_perm:[1,0,3,2] row_mask:0xf bank_mask:0xf
	v_add_f32_dpp v115, v115, v115 quad_perm:[1,0,3,2] row_mask:0xf bank_mask:0xf
	v_add_f32_dpp v112, v112, v112 quad_perm:[2,3,0,1] row_mask:0xf bank_mask:0xf
	v_add_f32_dpp v113, v113, v113 quad_perm:[2,3,0,1] row_mask:0xf bank_mask:0xf
	v_add_f32_dpp v114, v114, v114 quad_perm:[2,3,0,1] row_mask:0xf bank_mask:0xf
	v_add_f32_dpp v115, v115, v115 quad_perm:[2,3,0,1] row_mask:0xf bank_mask:0xf
	v_add_f32_dpp v112, v112, v112 row_half_mirror row_mask:0xf bank_mask:0xf
	v_add_f32_dpp v113, v113, v113 row_half_mirror row_mask:0xf bank_mask:0xf
	v_add_f32_dpp v114, v114, v114 row_half_mirror row_mask:0xf bank_mask:0xf
	v_add_f32_dpp v115, v115, v115 row_half_mirror row_mask:0xf bank_mask:0xf
	v_add_f32_dpp v112, v112, v112 row_mirror row_mask:0xf bank_mask:0xf
	v_add_f32_dpp v113, v113, v113 row_mirror row_mask:0xf bank_mask:0xf
	v_add_f32_dpp v114, v114, v114 row_mirror row_mask:0xf bank_mask:0xf
	v_add_f32_dpp v115, v115, v115 row_mirror row_mask:0xf bank_mask:0xf
	s_nop 1
	v_readlane_b32 s82, v112, 0
	v_readlane_b32 s83, v112, 16
	v_readlane_b32 s84, v112, 32
	v_readlane_b32 s85, v112, 48
	s_nop 1
	v_mov_b32_e32 v116, s82
	v_add_f32_e32 v116, s83, v116
	v_add_f32_e32 v116, s84, v116
	v_add_f32_e32 v116, s85, v116
	v_readlane_b32 s82, v113, 0
	v_readlane_b32 s83, v113, 16
	v_readlane_b32 s84, v113, 32
	v_readlane_b32 s85, v113, 48
	s_nop 1
	v_mov_b32_e32 v117, s82
	v_add_f32_e32 v117, s83, v117
	v_add_f32_e32 v117, s84, v117
	v_add_f32_e32 v117, s85, v117
	v_readlane_b32 s82, v114, 0
	v_readlane_b32 s83, v114, 16
	v_readlane_b32 s84, v114, 32
	v_readlane_b32 s85, v114, 48
	s_nop 1
	v_mov_b32_e32 v118, s82
	v_add_f32_e32 v118, s83, v118
	v_add_f32_e32 v118, s84, v118
	v_add_f32_e32 v118, s85, v118
	v_readlane_b32 s82, v115, 0
	v_readlane_b32 s83, v115, 16
	v_readlane_b32 s84, v115, 32
	v_readlane_b32 s85, v115, 48
	s_nop 1
	v_mov_b32_e32 v119, s82
	v_add_f32_e32 v119, s83, v119
	v_add_f32_e32 v119, s84, v119
	v_add_f32_e32 v119, s85, v119
	s_mov_b32 s0, 0x3a800000
	v_fma_f32 v116, v116, s0, v153
	v_fma_f32 v117, v117, s0, v153
	v_fma_f32 v118, v118, s0, v153
	v_fma_f32 v119, v119, s0, v153
	v_rsq_f32_e32 v112, v116
	v_rsq_f32_e32 v113, v117
	v_rsq_f32_e32 v114, v118
	v_rsq_f32_e32 v115, v119
	s_waitcnt vmcnt(4)
	v_add_f32_e32 v80, 1.0, v80
	v_add_f32_e32 v81, 1.0, v81
	v_add_f32_e32 v82, 1.0, v82
	v_add_f32_e32 v83, 1.0, v83
	v_add_f32_e32 v84, 1.0, v84
	v_add_f32_e32 v85, 1.0, v85
	v_add_f32_e32 v86, 1.0, v86
	v_add_f32_e32 v87, 1.0, v87
	v_add_f32_e32 v88, 1.0, v88
	v_add_f32_e32 v89, 1.0, v89
	v_add_f32_e32 v90, 1.0, v90
	v_add_f32_e32 v91, 1.0, v91
	v_add_f32_e32 v92, 1.0, v92
	v_add_f32_e32 v93, 1.0, v93
	v_add_f32_e32 v94, 1.0, v94
	v_add_f32_e32 v95, 1.0, v95
	v_mul_f32_e32 v64, v64, v80
	v_mul_f32_e32 v65, v65, v81
	v_mul_f32_e32 v66, v66, v82
	v_mul_f32_e32 v67, v67, v83
	v_mul_f32_e32 v68, v68, v84
	v_mul_f32_e32 v69, v69, v85
	v_mul_f32_e32 v70, v70, v86
	v_mul_f32_e32 v71, v71, v87
	v_mul_f32_e32 v72, v72, v88
	v_mul_f32_e32 v73, v73, v89
	v_mul_f32_e32 v74, v74, v90
	v_mul_f32_e32 v75, v75, v91
	v_mul_f32_e32 v76, v76, v92
	v_mul_f32_e32 v77, v77, v93
	v_mul_f32_e32 v78, v78, v94
	v_mul_f32_e32 v79, v79, v95
	s_waitcnt vmcnt(0)
; DI unsigned pack2(float lo, float hi) { f32x2_t v = {lo, hi}; bf16x2_t r = __builtin_convertvector(v, bf16x2_t); return __builtin_bit_cast(unsigned, r); }
; DI void phase_norm(const Params& p, int layer, int which  , int nrows) {
;     ...
; #pragma unroll
;     for (int k = 0; k < 2; ++k) {
;       const float rstd = k == 0 ? rstd0 : rstd1;
; #pragma unroll
;       for (int i = 0; i < 4; ++i) {
;         const int col = 4 * (lane + 64 * i);
;         float y0 = v[k][i].x * rstd * gg[i].x * (1.f + s4[i].x) + h4[i].x;
;         float y1 = v[k][i].y * rstd * gg[i].y * (1.f + s4[i].y) + h4[i].y;
;         float y2 = v[k][i].z * rstd * gg[i].z * (1.f + s4[i].z) + h4[i].z;
;         float y3 = v[k][i].w * rstd * gg[i].w * (1.f + s4[i].w) + h4[i].w;
;         uint2 w; w.x = pack2(y0, y1); w.y = pack2(y2, y3);
;         *(uint2*)(H + (size_t)(row + k) * D + col) = w;
;       }
;     }
	v_mul_f32_e32 v0, v0, v112
	v_mul_f32_e32 v1, v1, v112
	v_mul_f32_e32 v2, v2, v112
	v_mul_f32_e32 v3, v3, v112
	v_fma_f32 v0, v0, v64, v96
	v_fma_f32 v1, v1, v65, v97
	v_fma_f32 v2, v2, v66, v98
	v_fma_f32 v3, v3, v67, v99
	v_cvt_pk_bf16_f32 v124, v0, v1
	v_cvt_pk_bf16_f32 v125, v2, v3
	global_store_dwordx2 v148, v[124:125], s[66:67]
	v_mul_f32_e32 v4, v4, v112
	v_mul_f32_e32 v5, v5, v112
	v_mul_f32_e32 v6, v6, v112
	v_mul_f32_e32 v7, v7, v112
	v_fma_f32 v4, v4, v68, v100
	v_fma_f32 v5, v5, v69, v101
	v_fma_f32 v6, v6, v70, v102
	v_fma_f32 v7, v7, v71, v103
	v_cvt_pk_bf16_f32 v126, v4, v5
	v_cvt_pk_bf16_f32 v127, v6, v7
	global_store_dwordx2 v149, v[126:127], s[66:67]
	v_mul_f32_e32 v8, v8, v112
	v_mul_f32_e32 v9, v9, v112
	v_mul_f32_e32 v10, v10, v112
	v_mul_f32_e32 v11, v11, v112
	v_fma_f32 v8, v8, v72, v104
	v_fma_f32 v9, v9, v73, v105
	v_fma_f32 v10, v10, v74, v106
	v_fma_f32 v11, v11, v75, v107
	v_cvt_pk_bf16_f32 v128, v8, v9
	v_cvt_pk_bf16_f32 v129, v10, v11
	global_store_dwordx2 v150, v[128:129], s[66:67]
	v_mul_f32_e32 v12, v12, v112
	v_mul_f32_e32 v13, v13, v112
	v_mul_f32_e32 v14, v14, v112
	v_mul_f32_e32 v15, v15, v112
	v_fma_f32 v12, v12, v76, v108
	v_fma_f32 v13, v13, v77, v109
	v_fma_f32 v14, v14, v78, v110
	v_fma_f32 v15, v15, v79, v111
	v_cvt_pk_bf16_f32 v130, v12, v13
	v_cvt_pk_bf16_f32 v131, v14, v15
	global_store_dwordx2 v151, v[130:131], s[66:67]
	v_mul_f32_e32 v16, v16, v113
	v_mul_f32_e32 v17, v17, v113
	v_mul_f32_e32 v18, v18, v113
	v_mul_f32_e32 v19, v19, v113
	v_fma_f32 v16, v16, v64, v96
	v_fma_f32 v17, v17, v65, v97
	v_fma_f32 v18, v18, v66, v98
	v_fma_f32 v19, v19, v67, v99
	v_cvt_pk_bf16_f32 v132, v16, v17
	v_cvt_pk_bf16_f32 v133, v18, v19
	global_store_dwordx2 v148, v[132:133], s[66:67] offset:64
	v_mul_f32_e32 v20, v20, v113
	v_mul_f32_e32 v21, v21, v113
	v_mul_f32_e32 v22, v22, v113
	v_mul_f32_e32 v23, v23, v113
	v_fma_f32 v20, v20, v68, v100
	v_fma_f32 v21, v21, v69, v101
	v_fma_f32 v22, v22, v70, v102
	v_fma_f32 v23, v23, v71, v103
	v_cvt_pk_bf16_f32 v134, v20, v21
	v_cvt_pk_bf16_f32 v135, v22, v23
	global_store_dwordx2 v149, v[134:135], s[66:67] offset:64
	v_mul_f32_e32 v24, v24, v113
	v_mul_f32_e32 v25, v25, v113
	v_mul_f32_e32 v26, v26, v113
	v_mul_f32_e32 v27, v27, v113
	v_fma_f32 v24, v24, v72, v104
	v_fma_f32 v25, v25, v73, v105
	v_fma_f32 v26, v26, v74, v106
	v_fma_f32 v27, v27, v75, v107
	v_cvt_pk_bf16_f32 v124, v24, v25
	v_cvt_pk_bf16_f32 v125, v26, v27
	global_store_dwordx2 v150, v[124:125], s[66:67] offset:64
	v_mul_f32_e32 v28, v28, v113
	v_mul_f32_e32 v29, v29, v113
	v_mul_f32_e32 v30, v30, v113
	v_mul_f32_e32 v31, v31, v113
	v_fma_f32 v28, v28, v76, v108
	v_fma_f32 v29, v29, v77, v109
	v_fma_f32 v30, v30, v78, v110
	v_fma_f32 v31, v31, v79, v111
	v_cvt_pk_bf16_f32 v126, v28, v29
	v_cvt_pk_bf16_f32 v127, v30, v31
	global_store_dwordx2 v151, v[126:127], s[66:67] offset:64
	v_mul_f32_e32 v32, v32, v114
	v_mul_f32_e32 v33, v33, v114
	v_mul_f32_e32 v34, v34, v114
	v_mul_f32_e32 v35, v35, v114
	v_fma_f32 v32, v32, v64, v96
	v_fma_f32 v33, v33, v65, v97
	v_fma_f32 v34, v34, v66, v98
	v_fma_f32 v35, v35, v67, v99
	v_cvt_pk_bf16_f32 v128, v32, v33
	v_cvt_pk_bf16_f32 v129, v34, v35
	global_store_dwordx2 v148, v[128:129], s[66:67] offset:128
	v_mul_f32_e32 v36, v36, v114
	v_mul_f32_e32 v37, v37, v114
	v_mul_f32_e32 v38, v38, v114
	v_mul_f32_e32 v39, v39, v114
	v_fma_f32 v36, v36, v68, v100
	v_fma_f32 v37, v37, v69, v101
	v_fma_f32 v38, v38, v70, v102
	v_fma_f32 v39, v39, v71, v103
	v_cvt_pk_bf16_f32 v130, v36, v37
	v_cvt_pk_bf16_f32 v131, v38, v39
	global_store_dwordx2 v149, v[130:131], s[66:67] offset:128
	v_mul_f32_e32 v40, v40, v114
	v_mul_f32_e32 v41, v41, v114
	v_mul_f32_e32 v42, v42, v114
	v_mul_f32_e32 v43, v43, v114
	v_fma_f32 v40, v40, v72, v104
	v_fma_f32 v41, v41, v73, v105
	v_fma_f32 v42, v42, v74, v106
	v_fma_f32 v43, v43, v75, v107
	v_cvt_pk_bf16_f32 v132, v40, v41
	v_cvt_pk_bf16_f32 v133, v42, v43
	global_store_dwordx2 v150, v[132:133], s[66:67] offset:128
	v_mul_f32_e32 v44, v44, v114
	v_mul_f32_e32 v45, v45, v114
	v_mul_f32_e32 v46, v46, v114
	v_mul_f32_e32 v47, v47, v114
	v_fma_f32 v44, v44, v76, v108
	v_fma_f32 v45, v45, v77, v109
	v_fma_f32 v46, v46, v78, v110
	v_fma_f32 v47, v47, v79, v111
	v_cvt_pk_bf16_f32 v134, v44, v45
	v_cvt_pk_bf16_f32 v135, v46, v47
	global_store_dwordx2 v151, v[134:135], s[66:67] offset:128
	v_mul_f32_e32 v48, v48, v115
	v_mul_f32_e32 v49, v49, v115
	v_mul_f32_e32 v50, v50, v115
	v_mul_f32_e32 v51, v51, v115
	v_fma_f32 v48, v48, v64, v96
	v_fma_f32 v49, v49, v65, v97
	v_fma_f32 v50, v50, v66, v98
	v_fma_f32 v51, v51, v67, v99
	v_cvt_pk_bf16_f32 v124, v48, v49
	v_cvt_pk_bf16_f32 v125, v50, v51
	global_store_dwordx2 v148, v[124:125], s[66:67] offset:192
	v_mul_f32_e32 v52, v52, v115
	v_mul_f32_e32 v53, v53, v115
	v_mul_f32_e32 v54, v54, v115
	v_mul_f32_e32 v55, v55, v115
	v_fma_f32 v52, v52, v68, v100
	v_fma_f32 v53, v53, v69, v101
	v_fma_f32 v54, v54, v70, v102
	v_fma_f32 v55, v55, v71, v103
	v_cvt_pk_bf16_f32 v126, v52, v53
	v_cvt_pk_bf16_f32 v127, v54, v55
	global_store_dwordx2 v149, v[126:127], s[66:67] offset:192
	v_mul_f32_e32 v56, v56, v115
	v_mul_f32_e32 v57, v57, v115
	v_mul_f32_e32 v58, v58, v115
	v_mul_f32_e32 v59, v59, v115
	v_fma_f32 v56, v56, v72, v104
	v_fma_f32 v57, v57, v73, v105
	v_fma_f32 v58, v58, v74, v106
	v_fma_f32 v59, v59, v75, v107
	v_cvt_pk_bf16_f32 v128, v56, v57
	v_cvt_pk_bf16_f32 v129, v58, v59
	global_store_dwordx2 v150, v[128:129], s[66:67] offset:192
	v_mul_f32_e32 v60, v60, v115
	v_mul_f32_e32 v61, v61, v115
	v_mul_f32_e32 v62, v62, v115
	v_mul_f32_e32 v63, v63, v115
	v_fma_f32 v60, v60, v76, v108
	v_fma_f32 v61, v61, v77, v109
	v_fma_f32 v62, v62, v78, v110
	v_fma_f32 v63, v63, v79, v111
	v_cvt_pk_bf16_f32 v130, v60, v61
	v_cvt_pk_bf16_f32 v131, v62, v63
	global_store_dwordx2 v151, v[130:131], s[66:67] offset:192
	s_add_u32 s54, s54, s56
	s_branch .Lnm_loop_5
; DI int get_tid() { int t = threadIdx.x; asm volatile("" : "+v"(t)); return t; }
; DI void phase_norm(const Params& p, int layer, int which  , int nrows) {
;   const int lane = get_tid() & 63, gw = blockIdx.x * 4 + (get_tid() >> 6), nw = gridDim.x * 4;
.Lnm_done_6:
	s_mov_b32 s100, s52
	v_readlane_b32 s52, v254, 0
	v_readlane_b32 s53, v254, 1
	v_readlane_b32 s54, v254, 2
	v_readlane_b32 s55, v254, 3
	v_readlane_b32 s56, v254, 4
	v_readlane_b32 s57, v254, 5
	v_readlane_b32 s58, v254, 6
	v_readlane_b32 s59, v254, 7
	v_readlane_b32 s60, v254, 8
	v_readlane_b32 s61, v254, 9
	v_readlane_b32 s62, v254, 10
	v_readlane_b32 s63, v254, 11
	v_readlane_b32 s64, v254, 12
	v_readlane_b32 s65, v254, 13
	v_readlane_b32 s66, v254, 14
	v_readlane_b32 s67, v254, 15
	v_readlane_b32 s68, v254, 16
	v_readlane_b32 s69, v254, 17
	v_readlane_b32 s70, v254, 18
	v_readlane_b32 s71, v254, 19
	v_readlane_b32 s72, v254, 20
	v_readlane_b32 s73, v254, 21
	v_readlane_b32 s74, v254, 22
	v_readlane_b32 s75, v254, 23
	v_readlane_b32 s76, v254, 24
	v_readlane_b32 s77, v254, 25
	v_readlane_b32 s78, v254, 26
	v_readlane_b32 s79, v254, 27
	v_readlane_b32 s80, v254, 28
	v_readlane_b32 s81, v254, 29
	v_readlane_b32 s82, v254, 30
	v_readlane_b32 s83, v254, 31
	v_readlane_b32 s84, v254, 32
	v_readlane_b32 s85, v254, 33
	v_readlane_b32 s86, v254, 34
	v_readlane_b32 s87, v254, 35
	v_readlane_b32 s88, v254, 36
	v_readlane_b32 s89, v254, 37
	v_readlane_b32 s90, v254, 38
	v_readlane_b32 s91, v254, 39
	s_nop 3
	s_cmp_eq_u32 s100, 1
	s_cbranch_scc1 .Lnm_ret1
	s_branch .Lnm_ret0
